# prep: second back-to-back modulation GEMV item on a block reuses the silu(cond) table already in LDS
# baseline (speedup 1.0000x reference)
.Lprep_set:
	s_mov_b32 s100, 0
	s_sub_i32 s14, 0x111, s15
	s_mul_i32 s0, s15, 0x3a20
	s_mul_hi_i32 s1, s15, 0x3a20
	v_readlane_b32 s2, v251, 52
	v_readlane_b32 s3, v251, 53
	s_add_u32 s2, s2, s0
	s_addc_u32 s3, s3, s1
	s_cbranch_vccz .LBB0_778

.Lps_gen:
	s_sub_i32 s1, s73, 0x110
	s_cmpk_lt_i32 s1, 0x90
	s_cbranch_scc0 .Lps_gen2
	s_movk_i32 s101, 0x90
	s_cmpk_lt_i32 s15, 0x202
	s_cselect_b32 s101, 0xf0, s101
	s_cselect_b32 s100, 1, 0
	s_cmp_lt_i32 s15, 2
	s_cselect_b32 s101, 0x112, s101
	s_cselect_b32 s100, 0, s100
	s_movk_i32 s0, 0x321
	s_branch .Lps_adv

.LBB0_847:
	v_mov_b32_e32 v14, v175
	s_movk_i32 s0, 0x2400
	s_nop 0
	v_cmp_gt_i32_e32 vcc, s0, v14
	s_and_saveexec_b64 s[0:1], vcc
	v_readlane_b32 s56, v252, 7
	s_mov_b64 s[8:9], 0x400
	v_readlane_b32 s58, v252, 9
	v_readlane_b32 s59, v252, 10
	v_readlane_b32 s62, v252, 13
	v_readlane_b32 s63, v252, 14
	v_readlane_b32 s57, v252, 8
	v_readlane_b32 s60, v252, 11
	v_readlane_b32 s61, v252, 12
	v_readlane_b32 s64, v252, 15
	v_readlane_b32 s65, v252, 16
	v_readlane_b32 s66, v252, 17
	v_readlane_b32 s67, v252, 18
	v_readlane_b32 s68, v252, 19
	v_readlane_b32 s69, v252, 20
	v_readlane_b32 s70, v252, 21
	v_readlane_b32 s71, v252, 22
	s_cmp_eq_u32 s100, 1
	s_cbranch_scc1 .LBB0_850
	s_cbranch_execz .LBB0_850
	v_lshl_add_u32 v4, v14, 2, 0
	v_lshlrev_b32_e32 v2, 2, v14
	global_load_dword v16, v2, s[58:59]
	global_load_dword v17, v2, s[58:59] offset:1024
	global_load_dword v18, v2, s[58:59] offset:2048
	global_load_dword v19, v2, s[58:59] offset:3072
	v_add_u32_e32 v3, 0x1000, v2
	global_load_dword v20, v3, s[58:59]
	global_load_dword v21, v3, s[58:59] offset:1024
	global_load_dword v22, v3, s[58:59] offset:2048
	global_load_dword v23, v3, s[58:59] offset:3072
	v_add_u32_e32 v3, 0x2000, v2
	global_load_dword v24, v3, s[58:59]
	global_load_dword v25, v3, s[58:59] offset:1024
	global_load_dword v26, v3, s[58:59] offset:2048
	global_load_dword v27, v3, s[58:59] offset:3072
	v_add_u32_e32 v3, 0x3000, v2
	global_load_dword v28, v3, s[58:59]
	global_load_dword v29, v3, s[58:59] offset:1024
	global_load_dword v30, v3, s[58:59] offset:2048
	global_load_dword v31, v3, s[58:59] offset:3072
	v_add_u32_e32 v3, 0x4000, v2
	global_load_dword v32, v3, s[58:59]
	global_load_dword v33, v3, s[58:59] offset:1024
	global_load_dword v34, v3, s[58:59] offset:2048
	global_load_dword v35, v3, s[58:59] offset:3072
	v_add_u32_e32 v3, 0x5000, v2
	global_load_dword v36, v3, s[58:59]
	global_load_dword v37, v3, s[58:59] offset:1024
	global_load_dword v38, v3, s[58:59] offset:2048
	global_load_dword v39, v3, s[58:59] offset:3072
	v_add_u32_e32 v3, 0x6000, v2
	global_load_dword v40, v3, s[58:59]
	global_load_dword v41, v3, s[58:59] offset:1024
	global_load_dword v42, v3, s[58:59] offset:2048
	global_load_dword v43, v3, s[58:59] offset:3072
	v_add_u32_e32 v3, 0x7000, v2
	global_load_dword v44, v3, s[58:59]
	global_load_dword v45, v3, s[58:59] offset:1024
	global_load_dword v46, v3, s[58:59] offset:2048
	global_load_dword v47, v3, s[58:59] offset:3072
	global_load_dword v48, v2, s[62:63]
	global_load_dword v49, v2, s[62:63] offset:1024
	global_load_dword v50, v2, s[62:63] offset:2048
	global_load_dword v51, v2, s[62:63] offset:3072
	s_waitcnt vmcnt(35)
	v_mul_f32_e32 v6, 0xbfb8aa3b, v16
	v_exp_f32_e32 v6, v6
	s_nop 0
	v_add_f32_e32 v6, 1.0, v6
	v_div_scale_f32 v7, s[6:7], v6, v6, v16
	v_rcp_f32_e32 v8, v7
	v_div_scale_f32 v9, vcc, v16, v6, v16
	v_fma_f32 v10, -v7, v8, 1.0
	v_fmac_f32_e32 v8, v10, v8
	v_mul_f32_e32 v10, v9, v8
	v_fma_f32 v11, -v7, v10, v9
	v_fmac_f32_e32 v10, v11, v8
	v_fma_f32 v7, -v7, v10, v9
	v_div_fmas_f32 v7, v7, v8, v10
	v_div_fixup_f32 v0, v7, v6, v16
	ds_write_b32 v4, v0
	s_waitcnt vmcnt(34)
	v_mul_f32_e32 v6, 0xbfb8aa3b, v17
	v_exp_f32_e32 v6, v6
	s_nop 0
	v_add_f32_e32 v6, 1.0, v6
	v_div_scale_f32 v7, s[6:7], v6, v6, v17
	v_rcp_f32_e32 v8, v7
	v_div_scale_f32 v9, vcc, v17, v6, v17
	v_fma_f32 v10, -v7, v8, 1.0
	v_fmac_f32_e32 v8, v10, v8
	v_mul_f32_e32 v10, v9, v8
	v_fma_f32 v11, -v7, v10, v9
	v_fmac_f32_e32 v10, v11, v8
	v_fma_f32 v7, -v7, v10, v9
	v_div_fmas_f32 v7, v7, v8, v10
	v_div_fixup_f32 v0, v7, v6, v17
	ds_write_b32 v4, v0 offset:1024
	s_waitcnt vmcnt(33)
	v_mul_f32_e32 v6, 0xbfb8aa3b, v18
	v_exp_f32_e32 v6, v6
	s_nop 0
	v_add_f32_e32 v6, 1.0, v6
	v_div_scale_f32 v7, s[6:7], v6, v6, v18
	v_rcp_f32_e32 v8, v7
	v_div_scale_f32 v9, vcc, v18, v6, v18
	v_fma_f32 v10, -v7, v8, 1.0
	v_fmac_f32_e32 v8, v10, v8
	v_mul_f32_e32 v10, v9, v8
	v_fma_f32 v11, -v7, v10, v9
	v_fmac_f32_e32 v10, v11, v8
	v_fma_f32 v7, -v7, v10, v9
	v_div_fmas_f32 v7, v7, v8, v10
	v_div_fixup_f32 v0, v7, v6, v18
	ds_write_b32 v4, v0 offset:2048
	s_waitcnt vmcnt(32)
	v_mul_f32_e32 v6, 0xbfb8aa3b, v19
	v_exp_f32_e32 v6, v6
	s_nop 0
	v_add_f32_e32 v6, 1.0, v6
	v_div_scale_f32 v7, s[6:7], v6, v6, v19
	v_rcp_f32_e32 v8, v7
	v_div_scale_f32 v9, vcc, v19, v6, v19
	v_fma_f32 v10, -v7, v8, 1.0
	v_fmac_f32_e32 v8, v10, v8
	v_mul_f32_e32 v10, v9, v8
	v_fma_f32 v11, -v7, v10, v9
	v_fmac_f32_e32 v10, v11, v8
	v_fma_f32 v7, -v7, v10, v9
	v_div_fmas_f32 v7, v7, v8, v10
	v_div_fixup_f32 v0, v7, v6, v19
	ds_write_b32 v4, v0 offset:3072
	s_waitcnt vmcnt(31)
	v_mul_f32_e32 v6, 0xbfb8aa3b, v20
	v_exp_f32_e32 v6, v6
	s_nop 0
	v_add_f32_e32 v6, 1.0, v6
	v_div_scale_f32 v7, s[6:7], v6, v6, v20
	v_rcp_f32_e32 v8, v7
	v_div_scale_f32 v9, vcc, v20, v6, v20
	v_fma_f32 v10, -v7, v8, 1.0
	v_fmac_f32_e32 v8, v10, v8
	v_mul_f32_e32 v10, v9, v8
	v_fma_f32 v11, -v7, v10, v9
	v_fmac_f32_e32 v10, v11, v8
	v_fma_f32 v7, -v7, v10, v9
	v_div_fmas_f32 v7, v7, v8, v10
	v_div_fixup_f32 v0, v7, v6, v20
	ds_write_b32 v4, v0 offset:4096
	s_waitcnt vmcnt(30)
	v_mul_f32_e32 v6, 0xbfb8aa3b, v21
	v_exp_f32_e32 v6, v6
	s_nop 0
	v_add_f32_e32 v6, 1.0, v6
	v_div_scale_f32 v7, s[6:7], v6, v6, v21
	v_rcp_f32_e32 v8, v7
	v_div_scale_f32 v9, vcc, v21, v6, v21
	v_fma_f32 v10, -v7, v8, 1.0
	v_fmac_f32_e32 v8, v10, v8
	v_mul_f32_e32 v10, v9, v8
	v_fma_f32 v11, -v7, v10, v9
	v_fmac_f32_e32 v10, v11, v8
	v_fma_f32 v7, -v7, v10, v9
	v_div_fmas_f32 v7, v7, v8, v10
	v_div_fixup_f32 v0, v7, v6, v21
	ds_write_b32 v4, v0 offset:5120
	s_waitcnt vmcnt(29)
	v_mul_f32_e32 v6, 0xbfb8aa3b, v22
	v_exp_f32_e32 v6, v6
	s_nop 0
	v_add_f32_e32 v6, 1.0, v6
	v_div_scale_f32 v7, s[6:7], v6, v6, v22
	v_rcp_f32_e32 v8, v7
	v_div_scale_f32 v9, vcc, v22, v6, v22
	v_fma_f32 v10, -v7, v8, 1.0
	v_fmac_f32_e32 v8, v10, v8
	v_mul_f32_e32 v10, v9, v8
	v_fma_f32 v11, -v7, v10, v9
	v_fmac_f32_e32 v10, v11, v8
	v_fma_f32 v7, -v7, v10, v9
	v_div_fmas_f32 v7, v7, v8, v10
	v_div_fixup_f32 v0, v7, v6, v22
	ds_write_b32 v4, v0 offset:6144
	s_waitcnt vmcnt(28)
	v_mul_f32_e32 v6, 0xbfb8aa3b, v23
	v_exp_f32_e32 v6, v6
	s_nop 0
	v_add_f32_e32 v6, 1.0, v6
	v_div_scale_f32 v7, s[6:7], v6, v6, v23
	v_rcp_f32_e32 v8, v7
	v_div_scale_f32 v9, vcc, v23, v6, v23
	v_fma_f32 v10, -v7, v8, 1.0
	v_fmac_f32_e32 v8, v10, v8
	v_mul_f32_e32 v10, v9, v8
	v_fma_f32 v11, -v7, v10, v9
	v_fmac_f32_e32 v10, v11, v8
	v_fma_f32 v7, -v7, v10, v9
	v_div_fmas_f32 v7, v7, v8, v10
	v_div_fixup_f32 v0, v7, v6, v23
	ds_write_b32 v4, v0 offset:7168
	s_waitcnt vmcnt(27)
	v_mul_f32_e32 v6, 0xbfb8aa3b, v24
	v_exp_f32_e32 v6, v6
	s_nop 0
	v_add_f32_e32 v6, 1.0, v6
	v_div_scale_f32 v7, s[6:7], v6, v6, v24
	v_rcp_f32_e32 v8, v7
	v_div_scale_f32 v9, vcc, v24, v6, v24
	v_fma_f32 v10, -v7, v8, 1.0
	v_fmac_f32_e32 v8, v10, v8
	v_mul_f32_e32 v10, v9, v8
	v_fma_f32 v11, -v7, v10, v9
	v_fmac_f32_e32 v10, v11, v8
	v_fma_f32 v7, -v7, v10, v9
	v_div_fmas_f32 v7, v7, v8, v10
	v_div_fixup_f32 v0, v7, v6, v24
	ds_write_b32 v4, v0 offset:8192
	s_waitcnt vmcnt(26)
	v_mul_f32_e32 v6, 0xbfb8aa3b, v25
	v_exp_f32_e32 v6, v6
	s_nop 0
	v_add_f32_e32 v6, 1.0, v6
	v_div_scale_f32 v7, s[6:7], v6, v6, v25
	v_rcp_f32_e32 v8, v7
	v_div_scale_f32 v9, vcc, v25, v6, v25
	v_fma_f32 v10, -v7, v8, 1.0
	v_fmac_f32_e32 v8, v10, v8
	v_mul_f32_e32 v10, v9, v8
	v_fma_f32 v11, -v7, v10, v9
	v_fmac_f32_e32 v10, v11, v8
	v_fma_f32 v7, -v7, v10, v9
	v_div_fmas_f32 v7, v7, v8, v10
	v_div_fixup_f32 v0, v7, v6, v25
	ds_write_b32 v4, v0 offset:9216
	s_waitcnt vmcnt(25)
	v_mul_f32_e32 v6, 0xbfb8aa3b, v26
	v_exp_f32_e32 v6, v6
	s_nop 0
	v_add_f32_e32 v6, 1.0, v6
	v_div_scale_f32 v7, s[6:7], v6, v6, v26
	v_rcp_f32_e32 v8, v7
	v_div_scale_f32 v9, vcc, v26, v6, v26
	v_fma_f32 v10, -v7, v8, 1.0
	v_fmac_f32_e32 v8, v10, v8
	v_mul_f32_e32 v10, v9, v8
	v_fma_f32 v11, -v7, v10, v9
	v_fmac_f32_e32 v10, v11, v8
	v_fma_f32 v7, -v7, v10, v9
	v_div_fmas_f32 v7, v7, v8, v10
	v_div_fixup_f32 v0, v7, v6, v26
	ds_write_b32 v4, v0 offset:10240
	s_waitcnt vmcnt(24)
	v_mul_f32_e32 v6, 0xbfb8aa3b, v27
	v_exp_f32_e32 v6, v6
	s_nop 0
	v_add_f32_e32 v6, 1.0, v6
	v_div_scale_f32 v7, s[6:7], v6, v6, v27
	v_rcp_f32_e32 v8, v7
	v_div_scale_f32 v9, vcc, v27, v6, v27
	v_fma_f32 v10, -v7, v8, 1.0
	v_fmac_f32_e32 v8, v10, v8
	v_mul_f32_e32 v10, v9, v8
	v_fma_f32 v11, -v7, v10, v9
	v_fmac_f32_e32 v10, v11, v8
	v_fma_f32 v7, -v7, v10, v9
	v_div_fmas_f32 v7, v7, v8, v10
	v_div_fixup_f32 v0, v7, v6, v27
	ds_write_b32 v4, v0 offset:11264
	s_waitcnt vmcnt(23)
	v_mul_f32_e32 v6, 0xbfb8aa3b, v28
	v_exp_f32_e32 v6, v6
	s_nop 0
	v_add_f32_e32 v6, 1.0, v6
	v_div_scale_f32 v7, s[6:7], v6, v6, v28
	v_rcp_f32_e32 v8, v7
	v_div_scale_f32 v9, vcc, v28, v6, v28
	v_fma_f32 v10, -v7, v8, 1.0
	v_fmac_f32_e32 v8, v10, v8
	v_mul_f32_e32 v10, v9, v8
	v_fma_f32 v11, -v7, v10, v9
	v_fmac_f32_e32 v10, v11, v8
	v_fma_f32 v7, -v7, v10, v9
	v_div_fmas_f32 v7, v7, v8, v10
	v_div_fixup_f32 v0, v7, v6, v28
	ds_write_b32 v4, v0 offset:12288
	s_waitcnt vmcnt(22)
	v_mul_f32_e32 v6, 0xbfb8aa3b, v29
	v_exp_f32_e32 v6, v6
	s_nop 0
	v_add_f32_e32 v6, 1.0, v6
	v_div_scale_f32 v7, s[6:7], v6, v6, v29
	v_rcp_f32_e32 v8, v7
	v_div_scale_f32 v9, vcc, v29, v6, v29
	v_fma_f32 v10, -v7, v8, 1.0
	v_fmac_f32_e32 v8, v10, v8
	v_mul_f32_e32 v10, v9, v8
	v_fma_f32 v11, -v7, v10, v9
	v_fmac_f32_e32 v10, v11, v8
	v_fma_f32 v7, -v7, v10, v9
	v_div_fmas_f32 v7, v7, v8, v10
	v_div_fixup_f32 v0, v7, v6, v29
	ds_write_b32 v4, v0 offset:13312
	s_waitcnt vmcnt(21)
	v_mul_f32_e32 v6, 0xbfb8aa3b, v30
	v_exp_f32_e32 v6, v6
	s_nop 0
	v_add_f32_e32 v6, 1.0, v6
	v_div_scale_f32 v7, s[6:7], v6, v6, v30
	v_rcp_f32_e32 v8, v7
	v_div_scale_f32 v9, vcc, v30, v6, v30
	v_fma_f32 v10, -v7, v8, 1.0
	v_fmac_f32_e32 v8, v10, v8
	v_mul_f32_e32 v10, v9, v8
	v_fma_f32 v11, -v7, v10, v9
	v_fmac_f32_e32 v10, v11, v8
	v_fma_f32 v7, -v7, v10, v9
	v_div_fmas_f32 v7, v7, v8, v10
	v_div_fixup_f32 v0, v7, v6, v30
	ds_write_b32 v4, v0 offset:14336
	s_waitcnt vmcnt(20)
	v_mul_f32_e32 v6, 0xbfb8aa3b, v31
	v_exp_f32_e32 v6, v6
	s_nop 0
	v_add_f32_e32 v6, 1.0, v6
	v_div_scale_f32 v7, s[6:7], v6, v6, v31
	v_rcp_f32_e32 v8, v7
	v_div_scale_f32 v9, vcc, v31, v6, v31
	v_fma_f32 v10, -v7, v8, 1.0
	v_fmac_f32_e32 v8, v10, v8
	v_mul_f32_e32 v10, v9, v8
	v_fma_f32 v11, -v7, v10, v9
	v_fmac_f32_e32 v10, v11, v8
	v_fma_f32 v7, -v7, v10, v9
	v_div_fmas_f32 v7, v7, v8, v10
	v_div_fixup_f32 v0, v7, v6, v31
	ds_write_b32 v4, v0 offset:15360
	s_waitcnt vmcnt(19)
	v_mul_f32_e32 v6, 0xbfb8aa3b, v32
	v_exp_f32_e32 v6, v6
	s_nop 0
	v_add_f32_e32 v6, 1.0, v6
	v_div_scale_f32 v7, s[6:7], v6, v6, v32
	v_rcp_f32_e32 v8, v7
	v_div_scale_f32 v9, vcc, v32, v6, v32
	v_fma_f32 v10, -v7, v8, 1.0
	v_fmac_f32_e32 v8, v10, v8
	v_mul_f32_e32 v10, v9, v8
	v_fma_f32 v11, -v7, v10, v9
	v_fmac_f32_e32 v10, v11, v8
	v_fma_f32 v7, -v7, v10, v9
	v_div_fmas_f32 v7, v7, v8, v10
	v_div_fixup_f32 v0, v7, v6, v32
	ds_write_b32 v4, v0 offset:16384
	s_waitcnt vmcnt(18)
	v_mul_f32_e32 v6, 0xbfb8aa3b, v33
	v_exp_f32_e32 v6, v6
	s_nop 0
	v_add_f32_e32 v6, 1.0, v6
	v_div_scale_f32 v7, s[6:7], v6, v6, v33
	v_rcp_f32_e32 v8, v7
	v_div_scale_f32 v9, vcc, v33, v6, v33
	v_fma_f32 v10, -v7, v8, 1.0
	v_fmac_f32_e32 v8, v10, v8
	v_mul_f32_e32 v10, v9, v8
	v_fma_f32 v11, -v7, v10, v9
	v_fmac_f32_e32 v10, v11, v8
	v_fma_f32 v7, -v7, v10, v9
	v_div_fmas_f32 v7, v7, v8, v10
	v_div_fixup_f32 v0, v7, v6, v33
	ds_write_b32 v4, v0 offset:17408
	s_waitcnt vmcnt(17)
	v_mul_f32_e32 v6, 0xbfb8aa3b, v34
	v_exp_f32_e32 v6, v6
	s_nop 0
	v_add_f32_e32 v6, 1.0, v6
	v_div_scale_f32 v7, s[6:7], v6, v6, v34
	v_rcp_f32_e32 v8, v7
	v_div_scale_f32 v9, vcc, v34, v6, v34
	v_fma_f32 v10, -v7, v8, 1.0
	v_fmac_f32_e32 v8, v10, v8
	v_mul_f32_e32 v10, v9, v8
	v_fma_f32 v11, -v7, v10, v9
	v_fmac_f32_e32 v10, v11, v8
	v_fma_f32 v7, -v7, v10, v9
	v_div_fmas_f32 v7, v7, v8, v10
	v_div_fixup_f32 v0, v7, v6, v34
	ds_write_b32 v4, v0 offset:18432
	s_waitcnt vmcnt(16)
	v_mul_f32_e32 v6, 0xbfb8aa3b, v35
	v_exp_f32_e32 v6, v6
	s_nop 0
	v_add_f32_e32 v6, 1.0, v6
	v_div_scale_f32 v7, s[6:7], v6, v6, v35
	v_rcp_f32_e32 v8, v7
	v_div_scale_f32 v9, vcc, v35, v6, v35
	v_fma_f32 v10, -v7, v8, 1.0
	v_fmac_f32_e32 v8, v10, v8
	v_mul_f32_e32 v10, v9, v8
	v_fma_f32 v11, -v7, v10, v9
	v_fmac_f32_e32 v10, v11, v8
	v_fma_f32 v7, -v7, v10, v9
	v_div_fmas_f32 v7, v7, v8, v10
	v_div_fixup_f32 v0, v7, v6, v35
	ds_write_b32 v4, v0 offset:19456
	s_waitcnt vmcnt(15)
	v_mul_f32_e32 v6, 0xbfb8aa3b, v36
	v_exp_f32_e32 v6, v6
	s_nop 0
	v_add_f32_e32 v6, 1.0, v6
	v_div_scale_f32 v7, s[6:7], v6, v6, v36
	v_rcp_f32_e32 v8, v7
	v_div_scale_f32 v9, vcc, v36, v6, v36
	v_fma_f32 v10, -v7, v8, 1.0
	v_fmac_f32_e32 v8, v10, v8
	v_mul_f32_e32 v10, v9, v8
	v_fma_f32 v11, -v7, v10, v9
	v_fmac_f32_e32 v10, v11, v8
	v_fma_f32 v7, -v7, v10, v9
	v_div_fmas_f32 v7, v7, v8, v10
	v_div_fixup_f32 v0, v7, v6, v36
	ds_write_b32 v4, v0 offset:20480
	s_waitcnt vmcnt(14)
	v_mul_f32_e32 v6, 0xbfb8aa3b, v37
	v_exp_f32_e32 v6, v6
	s_nop 0
	v_add_f32_e32 v6, 1.0, v6
	v_div_scale_f32 v7, s[6:7], v6, v6, v37
	v_rcp_f32_e32 v8, v7
	v_div_scale_f32 v9, vcc, v37, v6, v37
	v_fma_f32 v10, -v7, v8, 1.0
	v_fmac_f32_e32 v8, v10, v8
	v_mul_f32_e32 v10, v9, v8
	v_fma_f32 v11, -v7, v10, v9
	v_fmac_f32_e32 v10, v11, v8
	v_fma_f32 v7, -v7, v10, v9
	v_div_fmas_f32 v7, v7, v8, v10
	v_div_fixup_f32 v0, v7, v6, v37
	ds_write_b32 v4, v0 offset:21504
	s_waitcnt vmcnt(13)
	v_mul_f32_e32 v6, 0xbfb8aa3b, v38
	v_exp_f32_e32 v6, v6
	s_nop 0
	v_add_f32_e32 v6, 1.0, v6
	v_div_scale_f32 v7, s[6:7], v6, v6, v38
	v_rcp_f32_e32 v8, v7
	v_div_scale_f32 v9, vcc, v38, v6, v38
	v_fma_f32 v10, -v7, v8, 1.0
	v_fmac_f32_e32 v8, v10, v8
	v_mul_f32_e32 v10, v9, v8
	v_fma_f32 v11, -v7, v10, v9
	v_fmac_f32_e32 v10, v11, v8
	v_fma_f32 v7, -v7, v10, v9
	v_div_fmas_f32 v7, v7, v8, v10
	v_div_fixup_f32 v0, v7, v6, v38
	ds_write_b32 v4, v0 offset:22528
	s_waitcnt vmcnt(12)
	v_mul_f32_e32 v6, 0xbfb8aa3b, v39
	v_exp_f32_e32 v6, v6
	s_nop 0
	v_add_f32_e32 v6, 1.0, v6
	v_div_scale_f32 v7, s[6:7], v6, v6, v39
	v_rcp_f32_e32 v8, v7
	v_div_scale_f32 v9, vcc, v39, v6, v39
	v_fma_f32 v10, -v7, v8, 1.0
	v_fmac_f32_e32 v8, v10, v8
	v_mul_f32_e32 v10, v9, v8
	v_fma_f32 v11, -v7, v10, v9
	v_fmac_f32_e32 v10, v11, v8
	v_fma_f32 v7, -v7, v10, v9
	v_div_fmas_f32 v7, v7, v8, v10
	v_div_fixup_f32 v0, v7, v6, v39
	ds_write_b32 v4, v0 offset:23552
	s_waitcnt vmcnt(11)
	v_mul_f32_e32 v6, 0xbfb8aa3b, v40
	v_exp_f32_e32 v6, v6
	s_nop 0
	v_add_f32_e32 v6, 1.0, v6
	v_div_scale_f32 v7, s[6:7], v6, v6, v40
	v_rcp_f32_e32 v8, v7
	v_div_scale_f32 v9, vcc, v40, v6, v40
	v_fma_f32 v10, -v7, v8, 1.0
	v_fmac_f32_e32 v8, v10, v8
	v_mul_f32_e32 v10, v9, v8
	v_fma_f32 v11, -v7, v10, v9
	v_fmac_f32_e32 v10, v11, v8
	v_fma_f32 v7, -v7, v10, v9
	v_div_fmas_f32 v7, v7, v8, v10
	v_div_fixup_f32 v0, v7, v6, v40
	ds_write_b32 v4, v0 offset:24576
	s_waitcnt vmcnt(10)
	v_mul_f32_e32 v6, 0xbfb8aa3b, v41
	v_exp_f32_e32 v6, v6
	s_nop 0
	v_add_f32_e32 v6, 1.0, v6
	v_div_scale_f32 v7, s[6:7], v6, v6, v41
	v_rcp_f32_e32 v8, v7
	v_div_scale_f32 v9, vcc, v41, v6, v41
	v_fma_f32 v10, -v7, v8, 1.0
	v_fmac_f32_e32 v8, v10, v8
	v_mul_f32_e32 v10, v9, v8
	v_fma_f32 v11, -v7, v10, v9
	v_fmac_f32_e32 v10, v11, v8
	v_fma_f32 v7, -v7, v10, v9
	v_div_fmas_f32 v7, v7, v8, v10
	v_div_fixup_f32 v0, v7, v6, v41
	ds_write_b32 v4, v0 offset:25600
	s_waitcnt vmcnt(9)
	v_mul_f32_e32 v6, 0xbfb8aa3b, v42
	v_exp_f32_e32 v6, v6
	s_nop 0
	v_add_f32_e32 v6, 1.0, v6
	v_div_scale_f32 v7, s[6:7], v6, v6, v42
	v_rcp_f32_e32 v8, v7
	v_div_scale_f32 v9, vcc, v42, v6, v42
	v_fma_f32 v10, -v7, v8, 1.0
	v_fmac_f32_e32 v8, v10, v8
	v_mul_f32_e32 v10, v9, v8
	v_fma_f32 v11, -v7, v10, v9
	v_fmac_f32_e32 v10, v11, v8
	v_fma_f32 v7, -v7, v10, v9
	v_div_fmas_f32 v7, v7, v8, v10
	v_div_fixup_f32 v0, v7, v6, v42
	ds_write_b32 v4, v0 offset:26624
	s_waitcnt vmcnt(8)
	v_mul_f32_e32 v6, 0xbfb8aa3b, v43
	v_exp_f32_e32 v6, v6
	s_nop 0
	v_add_f32_e32 v6, 1.0, v6
	v_div_scale_f32 v7, s[6:7], v6, v6, v43
	v_rcp_f32_e32 v8, v7
	v_div_scale_f32 v9, vcc, v43, v6, v43
	v_fma_f32 v10, -v7, v8, 1.0
	v_fmac_f32_e32 v8, v10, v8
	v_mul_f32_e32 v10, v9, v8
	v_fma_f32 v11, -v7, v10, v9
	v_fmac_f32_e32 v10, v11, v8
	v_fma_f32 v7, -v7, v10, v9
	v_div_fmas_f32 v7, v7, v8, v10
	v_div_fixup_f32 v0, v7, v6, v43
	ds_write_b32 v4, v0 offset:27648
	s_waitcnt vmcnt(7)
	v_mul_f32_e32 v6, 0xbfb8aa3b, v44
	v_exp_f32_e32 v6, v6
	s_nop 0
	v_add_f32_e32 v6, 1.0, v6
	v_div_scale_f32 v7, s[6:7], v6, v6, v44
	v_rcp_f32_e32 v8, v7
	v_div_scale_f32 v9, vcc, v44, v6, v44
	v_fma_f32 v10, -v7, v8, 1.0
	v_fmac_f32_e32 v8, v10, v8
	v_mul_f32_e32 v10, v9, v8
	v_fma_f32 v11, -v7, v10, v9
	v_fmac_f32_e32 v10, v11, v8
	v_fma_f32 v7, -v7, v10, v9
	v_div_fmas_f32 v7, v7, v8, v10
	v_div_fixup_f32 v0, v7, v6, v44
	ds_write_b32 v4, v0 offset:28672
	s_waitcnt vmcnt(6)
	v_mul_f32_e32 v6, 0xbfb8aa3b, v45
	v_exp_f32_e32 v6, v6
	s_nop 0
	v_add_f32_e32 v6, 1.0, v6
	v_div_scale_f32 v7, s[6:7], v6, v6, v45
	v_rcp_f32_e32 v8, v7
	v_div_scale_f32 v9, vcc, v45, v6, v45
	v_fma_f32 v10, -v7, v8, 1.0
	v_fmac_f32_e32 v8, v10, v8
	v_mul_f32_e32 v10, v9, v8
	v_fma_f32 v11, -v7, v10, v9
	v_fmac_f32_e32 v10, v11, v8
	v_fma_f32 v7, -v7, v10, v9
	v_div_fmas_f32 v7, v7, v8, v10
	v_div_fixup_f32 v0, v7, v6, v45
	ds_write_b32 v4, v0 offset:29696
	s_waitcnt vmcnt(5)
	v_mul_f32_e32 v6, 0xbfb8aa3b, v46
	v_exp_f32_e32 v6, v6
	s_nop 0
	v_add_f32_e32 v6, 1.0, v6
	v_div_scale_f32 v7, s[6:7], v6, v6, v46
	v_rcp_f32_e32 v8, v7
	v_div_scale_f32 v9, vcc, v46, v6, v46
	v_fma_f32 v10, -v7, v8, 1.0
	v_fmac_f32_e32 v8, v10, v8
	v_mul_f32_e32 v10, v9, v8
	v_fma_f32 v11, -v7, v10, v9
	v_fmac_f32_e32 v10, v11, v8
	v_fma_f32 v7, -v7, v10, v9
	v_div_fmas_f32 v7, v7, v8, v10
	v_div_fixup_f32 v0, v7, v6, v46
	ds_write_b32 v4, v0 offset:30720
	s_waitcnt vmcnt(4)
	v_mul_f32_e32 v6, 0xbfb8aa3b, v47
	v_exp_f32_e32 v6, v6
	s_nop 0
	v_add_f32_e32 v6, 1.0, v6
	v_div_scale_f32 v7, s[6:7], v6, v6, v47
	v_rcp_f32_e32 v8, v7
	v_div_scale_f32 v9, vcc, v47, v6, v47
	v_fma_f32 v10, -v7, v8, 1.0
	v_fmac_f32_e32 v8, v10, v8
	v_mul_f32_e32 v10, v9, v8
	v_fma_f32 v11, -v7, v10, v9
	v_fmac_f32_e32 v10, v11, v8
	v_fma_f32 v7, -v7, v10, v9
	v_div_fmas_f32 v7, v7, v8, v10
	v_div_fixup_f32 v0, v7, v6, v47
	ds_write_b32 v4, v0 offset:31744
	s_waitcnt vmcnt(3)
	v_mul_f32_e32 v6, 0xbfb8aa3b, v48
	v_exp_f32_e32 v6, v6
	s_nop 0
	v_add_f32_e32 v6, 1.0, v6
	v_div_scale_f32 v7, s[6:7], v6, v6, v48
	v_rcp_f32_e32 v8, v7
	v_div_scale_f32 v9, vcc, v48, v6, v48
	v_fma_f32 v10, -v7, v8, 1.0
	v_fmac_f32_e32 v8, v10, v8
	v_mul_f32_e32 v10, v9, v8
	v_fma_f32 v11, -v7, v10, v9
	v_fmac_f32_e32 v10, v11, v8
	v_fma_f32 v7, -v7, v10, v9
	v_div_fmas_f32 v7, v7, v8, v10
	v_div_fixup_f32 v0, v7, v6, v48
	ds_write_b32 v4, v0 offset:32768
	s_waitcnt vmcnt(2)
	v_mul_f32_e32 v6, 0xbfb8aa3b, v49
	v_exp_f32_e32 v6, v6
	s_nop 0
	v_add_f32_e32 v6, 1.0, v6
	v_div_scale_f32 v7, s[6:7], v6, v6, v49
	v_rcp_f32_e32 v8, v7
	v_div_scale_f32 v9, vcc, v49, v6, v49
	v_fma_f32 v10, -v7, v8, 1.0
	v_fmac_f32_e32 v8, v10, v8
	v_mul_f32_e32 v10, v9, v8
	v_fma_f32 v11, -v7, v10, v9
	v_fmac_f32_e32 v10, v11, v8
	v_fma_f32 v7, -v7, v10, v9
	v_div_fmas_f32 v7, v7, v8, v10
	v_div_fixup_f32 v0, v7, v6, v49
	ds_write_b32 v4, v0 offset:33792
	s_waitcnt vmcnt(1)
	v_mul_f32_e32 v6, 0xbfb8aa3b, v50
	v_exp_f32_e32 v6, v6
	s_nop 0
	v_add_f32_e32 v6, 1.0, v6
	v_div_scale_f32 v7, s[6:7], v6, v6, v50
	v_rcp_f32_e32 v8, v7
	v_div_scale_f32 v9, vcc, v50, v6, v50
	v_fma_f32 v10, -v7, v8, 1.0
	v_fmac_f32_e32 v8, v10, v8
	v_mul_f32_e32 v10, v9, v8
	v_fma_f32 v11, -v7, v10, v9
	v_fmac_f32_e32 v10, v11, v8
	v_fma_f32 v7, -v7, v10, v9
	v_div_fmas_f32 v7, v7, v8, v10
	v_div_fixup_f32 v0, v7, v6, v50
	ds_write_b32 v4, v0 offset:34816
	s_waitcnt vmcnt(0)
	v_mul_f32_e32 v6, 0xbfb8aa3b, v51
	v_exp_f32_e32 v6, v6
	s_nop 0
	v_add_f32_e32 v6, 1.0, v6
	v_div_scale_f32 v7, s[6:7], v6, v6, v51
	v_rcp_f32_e32 v8, v7
	v_div_scale_f32 v9, vcc, v51, v6, v51
	v_fma_f32 v10, -v7, v8, 1.0
	v_fmac_f32_e32 v8, v10, v8
	v_mul_f32_e32 v10, v9, v8
	v_fma_f32 v11, -v7, v10, v9
	v_fmac_f32_e32 v10, v11, v8
	v_fma_f32 v7, -v7, v10, v9
	v_div_fmas_f32 v7, v7, v8, v10
	v_div_fixup_f32 v0, v7, v6, v51
	ds_write_b32 v4, v0 offset:35840
